# E2b prelude skew with the job offset derived from the run-time wave count (same schedule at 256 CUs)
# baseline (speedup 1.0000x reference)
; __device__ __forceinline__ unsigned cvt_pk_bf16(float lo, float hi) { unsigned r; asm("v_cvt_pk_bf16_f32 %0, %1, %2" : "=v"(r) : "v"(lo), "v"(hi)); return r; }
; template <int layer>
; __device__ __forceinline__ void run_layer(LAS unsigned char* lds, const XcdBarrier& xb) {
;     ...
;                 for (int job = gw; job < 12 * 512; job += NGW) {
;                     const int seq = job >> 9, ch = job & 511;
;                     const int S = seq < 8 ? 2048 : 4096; const size_t tok0 = seq < 8 ? (size_t)seq * 2048 : (size_t)TP + (size_t)(seq - 8) * 4096;
;                     const bf16_t* fp = FT + (size_t)ch * T + tok0;
;                     float a = 0.f;
;                     for (int s0 = lane * 8; s0 < S; s0 += 512) { const u32x4 v = *(const u32x4*)(fp + s0);
; #pragma unroll
;                         for (int e = 0; e < 4; ++e) a += bf_lo(v[e]) - bf_hi(v[e]); }
;                     a = wave_sum(a) * (S == 2048 ? 0.02209708691207961f : 0.015625f);
;                     if (lane == 0) { bf16_t* o = PQ + (tok0 + S / 2) * 1024 + (ch >> 7) * 256 + (ch & 127); o[0] = (bf16_t)(cvt_pk_bf16(a, 0.f) & 0xffffu); o[128] = 0; }
.LBB0_405:
	s_or_b64 exec, exec, s[4:5]
	s_mov_b64 s[0:1], s[92:93]
	s_barrier
	s_load_dwordx2 s[10:11], s[0:1], 0x88
	v_mov_b32_e32 v0, v254
	v_readlane_b32 s0, v255, 0
	v_ashrrev_i32_e32 v1, 6, v0
	s_nop 0
	v_add_u32_e32 v8, s0, v1
	v_subrev_u32_e32 v8, s40, v8
	v_add_u32_e32 v8, 0x400, v8
	s_movk_i32 s0, 0x1800
	v_cmp_gt_u32_e32 vcc, s0, v8
	s_and_saveexec_b64 s[8:9], vcc
	s_cbranch_execz .LBB0_416
	v_mbcnt_lo_u32_b32 v1, -1, 0
	v_mbcnt_hi_u32_b32 v1, -1, v1
	v_and_b32_e32 v2, 64, v1
	v_add_u32_e32 v2, 64, v2
	v_xor_b32_e32 v3, 1, v1
	v_cmp_lt_i32_e32 vcc, v3, v2
	v_lshrrev_b32_e32 v4, 6, v0
	v_and_b32_e32 v0, 63, v0
	v_cndmask_b32_e32 v3, v1, v3, vcc
	v_lshlrev_b32_e32 v10, 2, v3
	v_xor_b32_e32 v3, 2, v1
	v_cmp_lt_i32_e32 vcc, v3, v2
	v_lshlrev_b32_e32 v9, 3, v0
	s_mov_b64 s[0:1], 0x1ce00000
	v_cndmask_b32_e32 v3, v1, v3, vcc
	v_lshlrev_b32_e32 v11, 2, v3
	v_xor_b32_e32 v3, 4, v1
	v_cmp_lt_i32_e32 vcc, v3, v2
	s_mov_b64 s[20:21], 0
	s_mov_b64 s[22:23], 0x4000
	v_cndmask_b32_e32 v3, v1, v3, vcc
	v_lshlrev_b32_e32 v12, 2, v3
	v_xor_b32_e32 v3, 8, v1
	v_cmp_lt_i32_e32 vcc, v3, v2
	v_mov_b32_e32 v17, 0x1000
	v_mov_b32_e32 v18, 0x800
	v_cndmask_b32_e32 v3, v1, v3, vcc
	v_lshlrev_b32_e32 v13, 2, v3
	v_xor_b32_e32 v3, 16, v1
	v_cmp_lt_i32_e32 vcc, v3, v2
	s_mov_b64 s[24:25], 0x400
	v_mov_b32_e32 v19, 0x3c800000
	v_cndmask_b32_e32 v3, v1, v3, vcc
	v_lshlrev_b32_e32 v14, 2, v3
	v_xor_b32_e32 v3, 32, v1
	v_cmp_lt_i32_e32 vcc, v3, v2
	v_mov_b32_e32 v20, 0x3cb504f3
	s_nop 0
	v_cndmask_b32_e32 v1, v1, v3, vcc
	v_lshlrev_b32_e32 v15, 2, v1
	v_cmp_eq_u32_e32 vcc, 0, v0
	v_lshlrev_b32_e32 v0, 4, v0
	v_mov_b32_e32 v1, 0
	v_lshl_add_u64 v[2:3], s[36:37], 0, v[0:1]
	v_lshl_add_u64 v[2:3], v[2:3], 0, s[0:1]
	v_readlane_b32 s0, v255, 0
	s_movk_i32 s1, 0x17ff
	s_nop 0
	v_add_u16_e32 v16, s0, v4
	s_movk_i32 s0, 0x1ff
	s_branch .LBB0_408

; __device__ __forceinline__ unsigned cvt_pk_bf16(float lo, float hi) { unsigned r; asm("v_cvt_pk_bf16_f32 %0, %1, %2" : "=v"(r) : "v"(lo), "v"(hi)); return r; }
; template <int layer>
; __device__ __forceinline__ void run_layer(LAS unsigned char* lds, const XcdBarrier& xb) {
;     ...
;                 for (int job = gw; job < 12 * 512; job += NGW) {
;                     const int seq = job >> 9, ch = job & 511;
;                     const int S = seq < 8 ? 2048 : 4096; const size_t tok0 = seq < 8 ? (size_t)seq * 2048 : (size_t)TP + (size_t)(seq - 8) * 4096;
;                     const bf16_t* fp = FT + (size_t)ch * T + tok0;
;                     float a = 0.f;
;                     for (int s0 = lane * 8; s0 < S; s0 += 512) { const u32x4 v = *(const u32x4*)(fp + s0);
; #pragma unroll
;                         for (int e = 0; e < 4; ++e) a += bf_lo(v[e]) - bf_hi(v[e]); }
;                     a = wave_sum(a) * (S == 2048 ? 0.02209708691207961f : 0.015625f);
;                     if (lane == 0) { bf16_t* o = PQ + (tok0 + S / 2) * 1024 + (ch >> 7) * 256 + (ch & 127); o[0] = (bf16_t)(cvt_pk_bf16(a, 0.f) & 0xffffu); o[128] = 0; }
.LBB0_1158:
	s_or_b64 exec, exec, s[8:9]
	s_mov_b64 s[0:1], s[82:83]
	s_barrier
	s_load_dwordx2 s[16:17], s[0:1], 0x88
	v_mov_b32_e32 v0, v254
	v_readlane_b32 s0, v255, 0
	v_ashrrev_i32_e32 v1, 6, v0
	s_nop 0
	v_add_u32_e32 v8, s0, v1
	v_subrev_u32_e32 v8, s40, v8
	v_add_u32_e32 v8, 0x400, v8
	s_movk_i32 s0, 0x1800
	v_cmp_gt_u32_e32 vcc, s0, v8
	s_and_saveexec_b64 s[12:13], vcc
	s_cbranch_execz .LBB0_1169
	v_mbcnt_lo_u32_b32 v1, -1, 0
	v_mbcnt_hi_u32_b32 v1, -1, v1
	v_and_b32_e32 v2, 64, v1
	v_add_u32_e32 v2, 64, v2
	v_xor_b32_e32 v3, 1, v1
	v_cmp_lt_i32_e32 vcc, v3, v2
	v_lshrrev_b32_e32 v4, 6, v0
	v_and_b32_e32 v0, 63, v0
	v_cndmask_b32_e32 v3, v1, v3, vcc
	v_lshlrev_b32_e32 v10, 2, v3
	v_xor_b32_e32 v3, 2, v1
	v_cmp_lt_i32_e32 vcc, v3, v2
	v_lshlrev_b32_e32 v9, 3, v0
	s_mov_b64 s[0:1], 0x1ce00000
	v_cndmask_b32_e32 v3, v1, v3, vcc
	v_lshlrev_b32_e32 v11, 2, v3
	v_xor_b32_e32 v3, 4, v1
	v_cmp_lt_i32_e32 vcc, v3, v2
	s_mov_b64 s[18:19], 0
	v_mov_b32_e32 v17, 0x1000
	v_cndmask_b32_e32 v3, v1, v3, vcc
	v_lshlrev_b32_e32 v12, 2, v3
	v_xor_b32_e32 v3, 8, v1
	v_cmp_lt_i32_e32 vcc, v3, v2
	v_mov_b32_e32 v18, 0x800
	s_mov_b64 s[50:51], 0x400
	v_cndmask_b32_e32 v3, v1, v3, vcc
	v_lshlrev_b32_e32 v13, 2, v3
	v_xor_b32_e32 v3, 16, v1
	v_cmp_lt_i32_e32 vcc, v3, v2
	v_mov_b32_e32 v19, 0x3c800000
	v_mov_b32_e32 v20, 0x3cb504f3
	v_cndmask_b32_e32 v3, v1, v3, vcc
	v_lshlrev_b32_e32 v14, 2, v3
	v_xor_b32_e32 v3, 32, v1
	v_cmp_lt_i32_e32 vcc, v3, v2
	s_nop 1
	v_cndmask_b32_e32 v1, v1, v3, vcc
	v_lshlrev_b32_e32 v15, 2, v1
	v_cmp_eq_u32_e32 vcc, 0, v0
	v_lshlrev_b32_e32 v0, 4, v0
	v_mov_b32_e32 v1, 0
	v_lshl_add_u64 v[2:3], s[48:49], 0, v[0:1]
	v_lshl_add_u64 v[2:3], v[2:3], 0, s[0:1]
	v_readlane_b32 s0, v255, 0
	s_mov_b64 s[48:49], 0x4000
	s_movk_i32 s1, 0x17ff
	v_add_u16_e32 v16, s0, v4
	s_movk_i32 s0, 0x1ff
	s_branch .LBB0_1161
